# static priority raise (s_setprio 1) for waves 4-7 during phase E, reset at phase exit
# speedup vs baseline: 1.0046x; 1.0019x over previous
; DI void phaseE(int wv0, PP p, unsigned char* smem, int cidx) {
;   __shared__ int s_item;
;   int* ctr = (int*)(p->ws + OFF_CTR) + cidx;
;   for (;;) {
;     __syncthreads();
;     if (my_tid(wv0) == 0) s_item = atomicAdd(ctr, 1);
;     __syncthreads();
;     const int item = s_item;
;     if (item >= 1024 + 2048 + (NXT - NXT_A)) break;
;     if (item < 1024) nsa_item(wv0, p, item, smem);
;     else if (item < 1024 + 2048) s5_item<true>(wv0, p, item - 1024, smem);
;     else xpose_tile(wv0, p, NXT_A + (item - 3072), smem);
;   }
; }
.LBB0_722:
	s_cmp_ge_u32 s89, 4
	s_cbranch_scc0 .Lmy_prio_done
	s_setprio 1

; DI void phaseE(int wv0, PP p, unsigned char* smem, int cidx) {
;     ...
;   for (;;) {
;     __syncthreads();
;     if (my_tid(wv0) == 0) s_item = atomicAdd(ctr, 1);
;     __syncthreads();
;     const int item = s_item;
;     if (item >= 1024 + 2048 + (NXT - NXT_A)) break;
;     if (item < 1024) nsa_item(wv0, p, item, smem);
;     else if (item < 1024 + 2048) s5_item<true>(wv0, p, item - 1024, smem);
;     else xpose_tile(wv0, p, NXT_A + (item - 3072), smem);
;   }
; }
.LBB0_922:
	s_setprio 0
	v_readlane_b32 s90, v247, 3
	v_readlane_b32 s76, v247, 1
	v_readlane_b32 s48, v247, 7
	v_readlane_b32 s91, v247, 4
	v_readlane_b32 s94, v247, 9
	v_readlane_b32 s89, v247, 47
	v_readlane_b32 s82, v247, 0
	v_readlane_b32 s77, v247, 2
	v_readlane_b32 s49, v247, 8
